# v_ntwin + first K-loop iteration of every GEMM unit peeled (in-proj and out-proj): first MFMA on each accumulator takes SrcC=0, the 128 accumulator-zeroing v_mov per unit removed
# speedup vs baseline: 1.0174x; 1.0081x over previous
; #define PG8_STAGE(bufoff, gbase, voff) do { _Pragma("unroll") for (int _i = 0; _i < 2; ++_i) \
;         __builtin_amdgcn_global_load_lds((const unsigned*)((const char*)(gbase) + (voff)[_i]), (PG8_LAS unsigned*)(lds + (bufoff) + ldsw + _i * 8192), 16, 0, 0); } while (0)
; #define PG8_LDA(dst, b, h) do { _Pragma("unroll") for (int m = 0; m < 4; ++m) _Pragma("unroll") for (int k = 0; k < 2; ++k) dst[m][k] = *(const PG8_LAS bf16x8*)(lds + PG8_SA(b, h) + aoff + m * 2048 + k * 1024); } while (0)
; #define PG8_LDB(dst, b, h) do { _Pragma("unroll") for (int n = 0; n < 2; ++n) _Pragma("unroll") for (int k = 0; k < 2; ++k) dst[n][k] = *(const PG8_LAS bf16x8*)(lds + PG8_SB(b, h) + boff + n * 2048 + k * 1024); } while (0)
; #define PG8_WAIT_V(n) asm volatile("s_waitcnt vmcnt(" #n ")" ::: "memory")
; #define PG8_WAIT_L(n) asm volatile("s_waitcnt lgkmcnt(" #n ")" ::: "memory")
; #define PG8_BAR __builtin_amdgcn_s_barrier()
; #define PG8_SCHED __builtin_amdgcn_sched_barrier(0)
; template <class Epi, class Sched, bool ALIGN_EPI = false, bool SP2 = false>
; __device__ __forceinline__ void gemm_phase(PG8_LAS unsigned char* lds, const Gemm g, const Sched& S, const Epi& E) {
;     ...
;         const bool has_next = S.next(ui + 1, nxt);
;         const char* nA = has_next ? (const char*)g.A + (size_t)nxt.pm * tstep : cA; const char* nB = has_next ? (const char*)g.Bt + (size_t)nxt.pn * tstep : cB;
;         for (int t = 0; t < nt; t += 2) {
;             const bool last = (t == nt - 2);
;             const char* a1 = cA + (size_t)(t + 1) * kstep;
;             const char* a2 = last ? nA : cA + (size_t)(t + 2) * kstep; const char* b2 = last ? nB : cB + (size_t)(t + 2) * kstep;
;             const char* a3 = a2 + kstep; const char* b3 = b2 + kstep;
;             if (last && has_next) S.a_ready(nxt);
;             if constexpr (SP2) {
;             PG8_LDB(B0, 0, 0); PG8_LDB(B1, 0, 1); PG8_SCHED; PG8_LDA(At, 0, 0); PG8_STAGE(PG8_SA(1, 1), a1 + hstep, voffA);
;             PG8_WAIT_V(8); PG8_WAIT_L(0); PG8_BAR; PG8_MMA(0, 0, At, B0); PG8_MMA(0, 1, At, B1); PG8_BAR; PG8_SCHED;
;             PG8_LDA(At, 0, 1); PG8_STAGE(PG8_SB(0, 0), b2, voffB); PG8_STAGE(PG8_SB(0, 1), b2 + hstep, voffB); PG8_STAGE(PG8_SA(0, 0), a2, voffA);
;             PG8_WAIT_V(8); PG8_WAIT_L(0); PG8_BAR; PG8_MMA(1, 0, At, B0); PG8_MMA(1, 1, At, B1); PG8_BAR; PG8_SCHED;
.LBB0_410:
	s_ashr_i32 s35, s34, 31
	s_lshl_b64 s[0:1], s[34:35], 19
	s_add_u32 s38, s29, s0
	s_addc_u32 s39, s31, s1
	s_and_b64 s[0:1], s[10:11], exec
	s_cselect_b32 s0, s39, s5
	s_cselect_b32 s1, s38, s4
	s_ashr_i32 s37, s36, 31
	s_lshl_b64 s[40:41], s[36:37], 19
	s_add_u32 s40, s48, s40
	s_addc_u32 s41, s49, s41
	s_and_b64 s[44:45], s[10:11], exec
	s_cselect_b32 s9, s41, s7
	s_cselect_b32 s12, s40, s6
	s_add_u32 s4, s4, 0x40080
	s_addc_u32 s5, s5, 0
	s_add_u32 s33, s6, 0x100
	s_addc_u32 s35, s7, 0
	s_mov_b32 s37, -2
	ds_read_b128 v[130:133], v218
	ds_read_b128 v[134:137], v218 offset:1024
	ds_read_b128 v[138:141], v218 offset:2048
	ds_read_b128 v[142:145], v218 offset:3072
	ds_read_b128 v[146:149], v219
	ds_read_b128 v[150:153], v219 offset:1024
	ds_read_b128 v[154:157], v219 offset:2048
	ds_read_b128 v[158:161], v219 offset:3072
	s_add_u32 s6, s4, 0xfffc0080
	s_addc_u32 s7, s5, -1
	s_cmp_eq_u32 s37, 12
	s_cselect_b32 s45, s0, s7
	s_cselect_b32 s44, s1, s6
	s_cselect_b32 s7, s9, s35
	s_cselect_b32 s6, s12, s33
	v_lshl_add_u64 v[226:227], s[4:5], 0, v[188:189]
	s_add_i32 m0, s51, 0xc000
	s_waitcnt vmcnt(0)
	ds_read_b128 v[162:165], v220
	ds_read_b128 v[166:169], v220 offset:1024
	ds_read_b128 v[170:173], v220 offset:2048
	ds_read_b128 v[196:199], v220 offset:3072
	ds_read_b128 v[200:203], v220 offset:4096
	ds_read_b128 v[204:207], v220 offset:5120
	ds_read_b128 v[208:211], v220 offset:6144
	ds_read_b128 v[212:215], v220 offset:7168
	global_load_lds_dwordx4 v[226:227], off
	v_lshl_add_u64 v[226:227], s[4:5], 0, v[190:191]
	s_add_i32 m0, s51, 0xe000
	s_nop 0
	global_load_lds_dwordx4 v[226:227], off
	s_waitcnt vmcnt(8)
	s_waitcnt lgkmcnt(0)
	s_barrier
	s_setprio 1
	s_waitcnt lgkmcnt(0)
	v_mfma_f32_16x16x32_bf16 v[126:129], v[130:133], v[162:165], 0
	v_mfma_f32_16x16x32_bf16 v[122:125], v[138:141], v[162:165], 0
	v_mfma_f32_16x16x32_bf16 v[110:113], v[130:133], v[170:173], 0
	v_mfma_f32_16x16x32_bf16 v[106:109], v[138:141], v[170:173], 0
	v_mfma_f32_16x16x32_bf16 v[94:97], v[130:133], v[200:203], 0
	v_mfma_f32_16x16x32_bf16 v[90:93], v[138:141], v[200:203], 0
	v_mfma_f32_16x16x32_bf16 v[78:81], v[130:133], v[208:211], 0
	v_mfma_f32_16x16x32_bf16 v[74:77], v[138:141], v[208:211], 0
	v_mfma_f32_16x16x32_bf16 v[126:129], v[134:137], v[166:169], v[126:129]
	v_mfma_f32_16x16x32_bf16 v[122:125], v[142:145], v[166:169], v[122:125]
	v_mfma_f32_16x16x32_bf16 v[110:113], v[134:137], v[196:199], v[110:113]
	v_mfma_f32_16x16x32_bf16 v[106:109], v[142:145], v[196:199], v[106:109]
	v_mfma_f32_16x16x32_bf16 v[94:97], v[134:137], v[204:207], v[94:97]
	v_mfma_f32_16x16x32_bf16 v[90:93], v[142:145], v[204:207], v[90:93]
	v_mfma_f32_16x16x32_bf16 v[78:81], v[134:137], v[212:215], v[78:81]
	v_mfma_f32_16x16x32_bf16 v[74:77], v[142:145], v[212:215], v[74:77]
	s_setprio 0
	s_setprio 1
	v_mfma_f32_16x16x32_bf16 v[118:121], v[146:149], v[162:165], 0
	v_mfma_f32_16x16x32_bf16 v[114:117], v[154:157], v[162:165], 0
	v_mfma_f32_16x16x32_bf16 v[102:105], v[146:149], v[170:173], 0
	v_mfma_f32_16x16x32_bf16 v[98:101], v[154:157], v[170:173], 0
	v_mfma_f32_16x16x32_bf16 v[86:89], v[146:149], v[200:203], 0
	v_mfma_f32_16x16x32_bf16 v[82:85], v[154:157], v[200:203], 0
	v_mfma_f32_16x16x32_bf16 v[70:73], v[146:149], v[208:211], 0
	v_mfma_f32_16x16x32_bf16 v[66:69], v[154:157], v[208:211], 0
	v_mfma_f32_16x16x32_bf16 v[118:121], v[150:153], v[166:169], v[118:121]
	v_mfma_f32_16x16x32_bf16 v[114:117], v[158:161], v[166:169], v[114:117]
	v_mfma_f32_16x16x32_bf16 v[102:105], v[150:153], v[196:199], v[102:105]
	v_mfma_f32_16x16x32_bf16 v[98:101], v[158:161], v[196:199], v[98:101]
	v_mfma_f32_16x16x32_bf16 v[86:89], v[150:153], v[204:207], v[86:89]
	v_mfma_f32_16x16x32_bf16 v[82:85], v[158:161], v[204:207], v[82:85]
	v_mfma_f32_16x16x32_bf16 v[70:73], v[150:153], v[212:215], v[70:73]
	v_mfma_f32_16x16x32_bf16 v[66:69], v[158:161], v[212:215], v[66:69]
	s_setprio 0
	s_barrier
	s_add_i32 s43, s86, s50
	v_lshl_add_u64 v[226:227], s[6:7], 0, v[178:179]
	s_mov_b32 m0, s43
	ds_read_b128 v[162:165], v220 offset:16384
	ds_read_b128 v[166:169], v220 offset:17408
	ds_read_b128 v[170:173], v220 offset:18432
	ds_read_b128 v[196:199], v220 offset:19456
	ds_read_b128 v[200:203], v220 offset:20480
	ds_read_b128 v[204:207], v220 offset:21504
	ds_read_b128 v[208:211], v220 offset:22528
	ds_read_b128 v[212:215], v220 offset:23552
	global_load_lds_dwordx4 v[226:227], off
	s_add_i32 m0, s43, 0x2000
	s_add_u32 s46, s6, 0x40000
	v_lshl_add_u64 v[228:229], s[6:7], 0, v[182:183]
	s_addc_u32 s47, s7, 0
	s_add_i32 s43, s87, s50
	global_load_lds_dwordx4 v[228:229], off
	v_lshl_add_u64 v[230:231], s[46:47], 0, v[178:179]
	s_mov_b32 m0, s43
	v_lshl_add_u64 v[232:233], s[44:45], 0, v[180:181]
	global_load_lds_dwordx4 v[230:231], off
	v_lshl_add_u64 v[230:231], s[46:47], 0, v[182:183]
	s_add_i32 m0, s43, 0x2000
	s_nop 0
	global_load_lds_dwordx4 v[230:231], off
	v_lshl_add_u64 v[230:231], s[44:45], 0, v[176:177]
	s_mov_b32 m0, s51
	s_nop 0
	global_load_lds_dwordx4 v[230:231], off
	s_mov_b32 m0, s52
	s_nop 0
	global_load_lds_dwordx4 v[232:233], off
	s_waitcnt vmcnt(8)
	s_waitcnt lgkmcnt(0)
	s_barrier
; #define PG8_STAGE(bufoff, gbase, voff) do { _Pragma("unroll") for (int _i = 0; _i < 2; ++_i) \
;         __builtin_amdgcn_global_load_lds((const unsigned*)((const char*)(gbase) + (voff)[_i]), (PG8_LAS unsigned*)(lds + (bufoff) + ldsw + _i * 8192), 16, 0, 0); } while (0)
; #define PG8_LDA(dst, b, h) do { _Pragma("unroll") for (int m = 0; m < 4; ++m) _Pragma("unroll") for (int k = 0; k < 2; ++k) dst[m][k] = *(const PG8_LAS bf16x8*)(lds + PG8_SA(b, h) + aoff + m * 2048 + k * 1024); } while (0)
; #define PG8_LDB(dst, b, h) do { _Pragma("unroll") for (int n = 0; n < 2; ++n) _Pragma("unroll") for (int k = 0; k < 2; ++k) dst[n][k] = *(const PG8_LAS bf16x8*)(lds + PG8_SB(b, h) + boff + n * 2048 + k * 1024); } while (0)
; #define PG8_MMA(ai, bj, At, Bt) do { __builtin_amdgcn_s_setprio(1); _Pragma("unroll") for (int m = 0; m < 4; ++m) _Pragma("unroll") for (int n = 0; n < 2; ++n) _Pragma("unroll") for (int k = 0; k < 2; ++k) \
;         acc[ai][bj][m][n] = __builtin_amdgcn_mfma_f32_16x16x32_bf16(Bt[n][k], At[m][k], acc[ai][bj][m][n], 0, 0, 0); __builtin_amdgcn_s_setprio(0); } while (0)
; #define PG8_WAIT_V(n) asm volatile("s_waitcnt vmcnt(" #n ")" ::: "memory")
; #define PG8_WAIT_L(n) asm volatile("s_waitcnt lgkmcnt(" #n ")" ::: "memory")
; #define PG8_BAR __builtin_amdgcn_s_barrier()
; #define PG8_SCHED __builtin_amdgcn_sched_barrier(0)
; template <class Epi, class Sched, bool ALIGN_EPI = false, bool SP2 = false>
; __device__ __forceinline__ void gemm_phase(PG8_LAS unsigned char* lds, const Gemm g, const Sched& S, const Epi& E) {
;     ...
;             PG8_WAIT_V(8); PG8_WAIT_L(0); PG8_BAR; PG8_MMA(1, 0, At, B0); PG8_MMA(1, 1, At, B1); PG8_BAR; PG8_SCHED;
;             PG8_LDB(B0, 1, 0); PG8_LDB(B1, 1, 1); PG8_SCHED; PG8_LDA(At, 1, 0); PG8_STAGE(PG8_SA(0, 1), a2 + hstep, voffA);
;             PG8_WAIT_V(8); PG8_WAIT_L(0); PG8_BAR; PG8_MMA(0, 0, At, B0); PG8_MMA(0, 1, At, B1); PG8_BAR; PG8_SCHED;
	s_setprio 1
	s_waitcnt lgkmcnt(0)
	v_mfma_f32_16x16x32_bf16 v[62:65], v[130:133], v[162:165], 0
	v_mfma_f32_16x16x32_bf16 v[58:61], v[138:141], v[162:165], 0
	v_mfma_f32_16x16x32_bf16 v[46:49], v[130:133], v[170:173], 0
	v_mfma_f32_16x16x32_bf16 v[42:45], v[138:141], v[170:173], 0
	v_mfma_f32_16x16x32_bf16 v[30:33], v[130:133], v[200:203], 0
	v_mfma_f32_16x16x32_bf16 v[26:29], v[138:141], v[200:203], 0
	v_mfma_f32_16x16x32_bf16 v[14:17], v[130:133], v[208:211], 0
	v_mfma_f32_16x16x32_bf16 v[10:13], v[138:141], v[208:211], 0
	v_mfma_f32_16x16x32_bf16 v[62:65], v[134:137], v[166:169], v[62:65]
	v_mfma_f32_16x16x32_bf16 v[58:61], v[142:145], v[166:169], v[58:61]
	v_mfma_f32_16x16x32_bf16 v[46:49], v[134:137], v[196:199], v[46:49]
	v_mfma_f32_16x16x32_bf16 v[42:45], v[142:145], v[196:199], v[42:45]
	v_mfma_f32_16x16x32_bf16 v[30:33], v[134:137], v[204:207], v[30:33]
	v_mfma_f32_16x16x32_bf16 v[26:29], v[142:145], v[204:207], v[26:29]
	v_mfma_f32_16x16x32_bf16 v[14:17], v[134:137], v[212:215], v[14:17]
	v_mfma_f32_16x16x32_bf16 v[10:13], v[142:145], v[212:215], v[10:13]
	s_setprio 0
	s_setprio 1
	v_mfma_f32_16x16x32_bf16 v[54:57], v[146:149], v[162:165], 0
	v_mfma_f32_16x16x32_bf16 v[50:53], v[154:157], v[162:165], 0
	v_mfma_f32_16x16x32_bf16 v[38:41], v[146:149], v[170:173], 0
	v_mfma_f32_16x16x32_bf16 v[34:37], v[154:157], v[170:173], 0
	v_mfma_f32_16x16x32_bf16 v[22:25], v[146:149], v[200:203], 0
	v_mfma_f32_16x16x32_bf16 v[18:21], v[154:157], v[200:203], 0
	v_mfma_f32_16x16x32_bf16 v[6:9], v[146:149], v[208:211], 0
	v_mfma_f32_16x16x32_bf16 v[2:5], v[154:157], v[208:211], 0
	v_mfma_f32_16x16x32_bf16 v[54:57], v[150:153], v[166:169], v[54:57]
	v_mfma_f32_16x16x32_bf16 v[50:53], v[158:161], v[166:169], v[50:53]
	v_mfma_f32_16x16x32_bf16 v[38:41], v[150:153], v[196:199], v[38:41]
	v_mfma_f32_16x16x32_bf16 v[34:37], v[158:161], v[196:199], v[34:37]
	v_mfma_f32_16x16x32_bf16 v[22:25], v[150:153], v[204:207], v[22:25]
	v_mfma_f32_16x16x32_bf16 v[18:21], v[158:161], v[204:207], v[18:21]
	v_mfma_f32_16x16x32_bf16 v[6:9], v[150:153], v[212:215], v[6:9]
	v_mfma_f32_16x16x32_bf16 v[2:5], v[158:161], v[212:215], v[2:5]
	s_setprio 0
	s_barrier
	s_add_i32 s43, 0, 0x18000
	s_add_i32 s46, 0, 0x1c000
	v_add_u32_e32 v142, s43, v217
	v_add_u32_e32 v158, s46, v217
	ds_read_b128 v[130:133], v142
	ds_read_b128 v[134:137], v142 offset:1024
	ds_read_b128 v[138:141], v142 offset:2048
	ds_read_b128 v[142:145], v142 offset:3072
	ds_read_b128 v[146:149], v158
	ds_read_b128 v[150:153], v158 offset:1024
	ds_read_b128 v[154:157], v158 offset:2048
	ds_read_b128 v[158:161], v158 offset:3072
	s_add_u32 s44, s44, 0x40000
	s_addc_u32 s45, s45, 0
	s_mov_b32 m0, s53
	v_lshl_add_u64 v[234:235], s[44:45], 0, v[176:177]
	ds_read_b128 v[162:165], v220 offset:32768
	ds_read_b128 v[166:169], v220 offset:33792
	ds_read_b128 v[170:173], v220 offset:34816
	ds_read_b128 v[196:199], v220 offset:35840
	ds_read_b128 v[200:203], v220 offset:36864
	ds_read_b128 v[204:207], v220 offset:37888
	ds_read_b128 v[208:211], v220 offset:38912
	ds_read_b128 v[212:215], v220 offset:39936
	global_load_lds_dwordx4 v[234:235], off
	v_lshl_add_u64 v[234:235], s[44:45], 0, v[180:181]
	s_mov_b32 m0, s54
	s_nop 0
	global_load_lds_dwordx4 v[234:235], off
	s_waitcnt vmcnt(8)
	s_waitcnt lgkmcnt(0)
	s_barrier
	s_setprio 1
	s_waitcnt lgkmcnt(0)
	v_mfma_f32_16x16x32_bf16 v[126:129], v[130:133], v[162:165], v[126:129]
	v_mfma_f32_16x16x32_bf16 v[122:125], v[138:141], v[162:165], v[122:125]
	v_mfma_f32_16x16x32_bf16 v[110:113], v[130:133], v[170:173], v[110:113]
	v_mfma_f32_16x16x32_bf16 v[106:109], v[138:141], v[170:173], v[106:109]
	v_mfma_f32_16x16x32_bf16 v[94:97], v[130:133], v[200:203], v[94:97]
	v_mfma_f32_16x16x32_bf16 v[90:93], v[138:141], v[200:203], v[90:93]
	v_mfma_f32_16x16x32_bf16 v[78:81], v[130:133], v[208:211], v[78:81]
	v_mfma_f32_16x16x32_bf16 v[74:77], v[138:141], v[208:211], v[74:77]
	v_mfma_f32_16x16x32_bf16 v[126:129], v[134:137], v[166:169], v[126:129]
	v_mfma_f32_16x16x32_bf16 v[122:125], v[142:145], v[166:169], v[122:125]
	v_mfma_f32_16x16x32_bf16 v[110:113], v[134:137], v[196:199], v[110:113]
	v_mfma_f32_16x16x32_bf16 v[106:109], v[142:145], v[196:199], v[106:109]
	v_mfma_f32_16x16x32_bf16 v[94:97], v[134:137], v[204:207], v[94:97]
	v_mfma_f32_16x16x32_bf16 v[90:93], v[142:145], v[204:207], v[90:93]
	v_mfma_f32_16x16x32_bf16 v[78:81], v[134:137], v[212:215], v[78:81]
	v_mfma_f32_16x16x32_bf16 v[74:77], v[142:145], v[212:215], v[74:77]
	s_setprio 0
	s_setprio 1
	v_mfma_f32_16x16x32_bf16 v[118:121], v[146:149], v[162:165], v[118:121]
	v_mfma_f32_16x16x32_bf16 v[114:117], v[154:157], v[162:165], v[114:117]
	v_mfma_f32_16x16x32_bf16 v[102:105], v[146:149], v[170:173], v[102:105]
	v_mfma_f32_16x16x32_bf16 v[98:101], v[154:157], v[170:173], v[98:101]
	v_mfma_f32_16x16x32_bf16 v[86:89], v[146:149], v[200:203], v[86:89]
	v_mfma_f32_16x16x32_bf16 v[82:85], v[154:157], v[200:203], v[82:85]
	v_mfma_f32_16x16x32_bf16 v[70:73], v[146:149], v[208:211], v[70:73]
	v_mfma_f32_16x16x32_bf16 v[66:69], v[154:157], v[208:211], v[66:69]
	v_mfma_f32_16x16x32_bf16 v[118:121], v[150:153], v[166:169], v[118:121]
	v_mfma_f32_16x16x32_bf16 v[114:117], v[158:161], v[166:169], v[114:117]
	v_mfma_f32_16x16x32_bf16 v[102:105], v[150:153], v[196:199], v[102:105]
	v_mfma_f32_16x16x32_bf16 v[98:101], v[158:161], v[196:199], v[98:101]
	v_mfma_f32_16x16x32_bf16 v[86:89], v[150:153], v[204:207], v[86:89]
	v_mfma_f32_16x16x32_bf16 v[82:85], v[158:161], v[204:207], v[82:85]
	v_mfma_f32_16x16x32_bf16 v[70:73], v[150:153], v[212:215], v[70:73]
	v_mfma_f32_16x16x32_bf16 v[66:69], v[158:161], v[212:215], v[66:69]
	s_setprio 0
	s_barrier
; #define PG8_STAGE(bufoff, gbase, voff) do { _Pragma("unroll") for (int _i = 0; _i < 2; ++_i) \
;         __builtin_amdgcn_global_load_lds((const unsigned*)((const char*)(gbase) + (voff)[_i]), (PG8_LAS unsigned*)(lds + (bufoff) + ldsw + _i * 8192), 16, 0, 0); } while (0)
; #define PG8_LDA(dst, b, h) do { _Pragma("unroll") for (int m = 0; m < 4; ++m) _Pragma("unroll") for (int k = 0; k < 2; ++k) dst[m][k] = *(const PG8_LAS bf16x8*)(lds + PG8_SA(b, h) + aoff + m * 2048 + k * 1024); } while (0)
; #define PG8_MMA(ai, bj, At, Bt) do { __builtin_amdgcn_s_setprio(1); _Pragma("unroll") for (int m = 0; m < 4; ++m) _Pragma("unroll") for (int n = 0; n < 2; ++n) _Pragma("unroll") for (int k = 0; k < 2; ++k) \
;         acc[ai][bj][m][n] = __builtin_amdgcn_mfma_f32_16x16x32_bf16(Bt[n][k], At[m][k], acc[ai][bj][m][n], 0, 0, 0); __builtin_amdgcn_s_setprio(0); } while (0)
; #define PG8_WAIT_V(n) asm volatile("s_waitcnt vmcnt(" #n ")" ::: "memory")
; #define PG8_WAIT_L(n) asm volatile("s_waitcnt lgkmcnt(" #n ")" ::: "memory")
; #define PG8_BAR __builtin_amdgcn_s_barrier()
; #define PG8_SCHED __builtin_amdgcn_sched_barrier(0)
; template <class Epi, class Sched, bool ALIGN_EPI = false, bool SP2 = false>
; __device__ __forceinline__ void gemm_phase(PG8_LAS unsigned char* lds, const Gemm g, const Sched& S, const Epi& E) {
;     ...
;         for (int t = 0; t < nt; t += 2) {
;             const bool last = (t == nt - 2);
;             const char* a1 = cA + (size_t)(t + 1) * kstep;
;             const char* a2 = last ? nA : cA + (size_t)(t + 2) * kstep; const char* b2 = last ? nB : cB + (size_t)(t + 2) * kstep;
;     ...
;             PG8_LDA(At, 1, 1); PG8_STAGE(PG8_SB(1, 0), b3, voffB); PG8_STAGE(PG8_SB(1, 1), b3 + hstep, voffB); PG8_STAGE(PG8_SA(1, 0), a3, voffA);
;             PG8_WAIT_V(8); PG8_WAIT_L(0); PG8_BAR; PG8_MMA(1, 0, At, B0); PG8_MMA(1, 1, At, B1); PG8_BAR; PG8_SCHED;
	s_add_i32 s43, s43, s50
	v_lshl_add_u64 v[226:227], v[226:227], 0, s[20:21]
	s_mov_b32 m0, s43
	ds_read_b128 v[162:165], v220 offset:49152
	ds_read_b128 v[166:169], v220 offset:50176
	ds_read_b128 v[170:173], v220 offset:51200
	ds_read_b128 v[196:199], v220 offset:52224
	ds_read_b128 v[200:203], v220 offset:53248
	ds_read_b128 v[204:207], v220 offset:54272
	ds_read_b128 v[208:211], v220 offset:55296
	ds_read_b128 v[212:215], v220 offset:56320
	global_load_lds_dwordx4 v[226:227], off
	s_add_i32 m0, s43, 0x2000
	s_add_u32 s6, s6, 0x40080
	v_lshl_add_u64 v[226:227], v[228:229], 0, s[20:21]
	s_addc_u32 s7, s7, 0
	s_add_i32 s43, s46, s50
	global_load_lds_dwordx4 v[226:227], off
	v_lshl_add_u64 v[226:227], s[6:7], 0, v[178:179]
	s_mov_b32 m0, s43
	s_nop 0
	global_load_lds_dwordx4 v[226:227], off
	v_lshl_add_u64 v[226:227], s[6:7], 0, v[182:183]
	s_add_i32 m0, s43, 0x2000
	s_nop 0
	global_load_lds_dwordx4 v[226:227], off
	v_lshl_add_u64 v[226:227], v[230:231], 0, s[20:21]
	s_mov_b32 m0, s67
	s_nop 0
	global_load_lds_dwordx4 v[226:227], off
	v_lshl_add_u64 v[226:227], v[232:233], 0, s[20:21]
	s_mov_b32 m0, s68
	s_nop 0
	global_load_lds_dwordx4 v[226:227], off
	s_waitcnt vmcnt(8)
	s_waitcnt lgkmcnt(0)
	s_barrier
	s_setprio 1
	s_waitcnt lgkmcnt(0)
	v_mfma_f32_16x16x32_bf16 v[62:65], v[130:133], v[162:165], v[62:65]
	v_mfma_f32_16x16x32_bf16 v[58:61], v[138:141], v[162:165], v[58:61]
	v_mfma_f32_16x16x32_bf16 v[46:49], v[130:133], v[170:173], v[46:49]
	v_mfma_f32_16x16x32_bf16 v[42:45], v[138:141], v[170:173], v[42:45]
	v_mfma_f32_16x16x32_bf16 v[30:33], v[130:133], v[200:203], v[30:33]
	v_mfma_f32_16x16x32_bf16 v[26:29], v[138:141], v[200:203], v[26:29]
	v_mfma_f32_16x16x32_bf16 v[14:17], v[130:133], v[208:211], v[14:17]
	v_mfma_f32_16x16x32_bf16 v[10:13], v[138:141], v[208:211], v[10:13]
	v_mfma_f32_16x16x32_bf16 v[62:65], v[134:137], v[166:169], v[62:65]
	v_mfma_f32_16x16x32_bf16 v[58:61], v[142:145], v[166:169], v[58:61]
	v_mfma_f32_16x16x32_bf16 v[46:49], v[134:137], v[196:199], v[46:49]
	v_mfma_f32_16x16x32_bf16 v[42:45], v[142:145], v[196:199], v[42:45]
	v_mfma_f32_16x16x32_bf16 v[30:33], v[134:137], v[204:207], v[30:33]
	v_mfma_f32_16x16x32_bf16 v[26:29], v[142:145], v[204:207], v[26:29]
	v_mfma_f32_16x16x32_bf16 v[14:17], v[134:137], v[212:215], v[14:17]
	v_mfma_f32_16x16x32_bf16 v[10:13], v[142:145], v[212:215], v[10:13]
	s_setprio 0
	s_setprio 1
	v_mfma_f32_16x16x32_bf16 v[54:57], v[146:149], v[162:165], v[54:57]
	v_mfma_f32_16x16x32_bf16 v[50:53], v[154:157], v[162:165], v[50:53]
	v_mfma_f32_16x16x32_bf16 v[38:41], v[146:149], v[170:173], v[38:41]
	v_mfma_f32_16x16x32_bf16 v[34:37], v[154:157], v[170:173], v[34:37]
	v_mfma_f32_16x16x32_bf16 v[22:25], v[146:149], v[200:203], v[22:25]
	v_mfma_f32_16x16x32_bf16 v[18:21], v[154:157], v[200:203], v[18:21]
	v_mfma_f32_16x16x32_bf16 v[6:9], v[146:149], v[208:211], v[6:9]
	v_mfma_f32_16x16x32_bf16 v[2:5], v[154:157], v[208:211], v[2:5]
	v_mfma_f32_16x16x32_bf16 v[54:57], v[150:153], v[166:169], v[54:57]
	v_mfma_f32_16x16x32_bf16 v[50:53], v[158:161], v[166:169], v[50:53]
	v_mfma_f32_16x16x32_bf16 v[38:41], v[150:153], v[196:199], v[38:41]
	v_mfma_f32_16x16x32_bf16 v[34:37], v[158:161], v[196:199], v[34:37]
	v_mfma_f32_16x16x32_bf16 v[22:25], v[150:153], v[204:207], v[22:25]
	v_mfma_f32_16x16x32_bf16 v[18:21], v[158:161], v[204:207], v[18:21]
	v_mfma_f32_16x16x32_bf16 v[6:9], v[150:153], v[212:215], v[6:9]
	v_mfma_f32_16x16x32_bf16 v[2:5], v[158:161], v[212:215], v[2:5]
	s_setprio 0
	s_barrier
	s_add_i32 s37, s37, 2
	s_add_u32 s4, s4, 0x100
	s_addc_u32 s5, s5, 0
	s_add_u32 s33, s33, 0x100
	s_addc_u32 s35, s35, 0
	s_cmp_gt_u32 s37, 13

; #define PG8_STAGE(bufoff, gbase, voff) do { _Pragma("unroll") for (int _i = 0; _i < 2; ++_i) \
;         __builtin_amdgcn_global_load_lds((const unsigned*)((const char*)(gbase) + (voff)[_i]), (PG8_LAS unsigned*)(lds + (bufoff) + ldsw + _i * 8192), 16, 0, 0); } while (0)
; #define PG8_LDA(dst, b, h) do { _Pragma("unroll") for (int m = 0; m < 4; ++m) _Pragma("unroll") for (int k = 0; k < 2; ++k) dst[m][k] = *(const PG8_LAS bf16x8*)(lds + PG8_SA(b, h) + aoff + m * 2048 + k * 1024); } while (0)
; #define PG8_LDB(dst, b, h) do { _Pragma("unroll") for (int n = 0; n < 2; ++n) _Pragma("unroll") for (int k = 0; k < 2; ++k) dst[n][k] = *(const PG8_LAS bf16x8*)(lds + PG8_SB(b, h) + boff + n * 2048 + k * 1024); } while (0)
; #define PG8_WAIT_V(n) asm volatile("s_waitcnt vmcnt(" #n ")" ::: "memory")
; #define PG8_WAIT_L(n) asm volatile("s_waitcnt lgkmcnt(" #n ")" ::: "memory")
; #define PG8_BAR __builtin_amdgcn_s_barrier()
; #define PG8_SCHED __builtin_amdgcn_sched_barrier(0)
; template <class Epi, class Sched, bool ALIGN_EPI = false, bool SP2 = false>
; __device__ __forceinline__ void gemm_phase(PG8_LAS unsigned char* lds, const Gemm g, const Sched& S, const Epi& E) {
;     ...
;         const bool has_next = S.next(ui + 1, nxt);
;         const char* nA = has_next ? (const char*)g.A + (size_t)nxt.pm * tstep : cA; const char* nB = has_next ? (const char*)g.Bt + (size_t)nxt.pn * tstep : cB;
;         for (int t = 0; t < nt; t += 2) {
;             const bool last = (t == nt - 2);
;             const char* a1 = cA + (size_t)(t + 1) * kstep;
;             const char* a2 = last ? nA : cA + (size_t)(t + 2) * kstep; const char* b2 = last ? nB : cB + (size_t)(t + 2) * kstep;
;             const char* a3 = a2 + kstep; const char* b3 = b2 + kstep;
;             if (last && has_next) S.a_ready(nxt);
;             if constexpr (SP2) {
;             PG8_LDB(B0, 0, 0); PG8_LDB(B1, 0, 1); PG8_SCHED; PG8_LDA(At, 0, 0); PG8_STAGE(PG8_SA(1, 1), a1 + hstep, voffA);
;             PG8_WAIT_V(8); PG8_WAIT_L(0); PG8_BAR; PG8_MMA(0, 0, At, B0); PG8_MMA(0, 1, At, B1); PG8_BAR; PG8_SCHED;
;             PG8_LDA(At, 0, 1); PG8_STAGE(PG8_SB(0, 0), b2, voffB); PG8_STAGE(PG8_SB(0, 1), b2 + hstep, voffB); PG8_STAGE(PG8_SA(0, 0), a2, voffA);
;             PG8_WAIT_V(8); PG8_WAIT_L(0); PG8_BAR; PG8_MMA(1, 0, At, B0); PG8_MMA(1, 1, At, B1); PG8_BAR; PG8_SCHED;
.LBB0_1235:
	s_ashr_i32 s15, s14, 31
	s_lshl_b64 s[18:19], s[14:15], 19
	s_add_u32 s18, s29, s18
	s_addc_u32 s19, s30, s19
	s_and_b64 s[20:21], s[0:1], exec
	s_cselect_b32 s5, s19, s23
	s_cselect_b32 s6, s18, s22
	s_ashr_i32 s17, s16, 31
	s_lshl_b64 s[20:21], s[16:17], 19
	s_add_u32 s20, s31, s20
	s_addc_u32 s21, s33, s21
	s_and_b64 s[26:27], s[0:1], exec
	s_cselect_b32 s15, s21, s25
	s_cselect_b32 s17, s20, s24
	s_add_u32 s22, s22, 0x40080
	s_addc_u32 s23, s23, 0
	s_add_u32 s59, s24, 0x100
	s_addc_u32 s60, s25, 0
	s_mov_b32 s61, -2
	ds_read_b128 v[128:131], v175
	ds_read_b128 v[132:135], v175 offset:1024
	ds_read_b128 v[136:139], v175 offset:2048
	ds_read_b128 v[140:143], v175 offset:3072
	ds_read_b128 v[144:147], v176
	ds_read_b128 v[148:151], v176 offset:1024
	ds_read_b128 v[164:167], v176 offset:2048
	ds_read_b128 v[168:171], v176 offset:3072
	s_add_u32 s24, s22, 0xfffc0080
	s_addc_u32 s25, s23, -1
	s_cmp_eq_u32 s61, 12
	s_cselect_b32 s27, s5, s25
	s_cselect_b32 s26, s6, s24
	s_cselect_b32 s25, s15, s60
	s_cselect_b32 s24, s17, s59
	v_lshl_add_u64 v[210:211], s[22:23], 0, v[156:157]
	s_add_i32 m0, s36, 0xc000
	ds_read_b128 v[178:181], v177
	ds_read_b128 v[182:185], v177 offset:1024
	ds_read_b128 v[186:189], v177 offset:2048
	ds_read_b128 v[190:193], v177 offset:3072
	ds_read_b128 v[194:197], v177 offset:4096
	ds_read_b128 v[198:201], v177 offset:5120
	ds_read_b128 v[202:205], v177 offset:6144
	ds_read_b128 v[206:209], v177 offset:7168
	global_load_lds_dwordx4 v[210:211], off
	v_lshl_add_u64 v[210:211], s[22:23], 0, v[158:159]
	s_add_i32 m0, s36, 0xe000
	s_nop 0
	global_load_lds_dwordx4 v[210:211], off
	s_waitcnt vmcnt(8)
	s_waitcnt lgkmcnt(0)
	s_barrier
	s_setprio 1
	s_waitcnt lgkmcnt(0)
	v_mfma_f32_16x16x32_bf16 v[124:127], v[128:131], v[178:181], 0
	v_mfma_f32_16x16x32_bf16 v[120:123], v[136:139], v[178:181], 0
	v_mfma_f32_16x16x32_bf16 v[108:111], v[128:131], v[186:189], 0
	v_mfma_f32_16x16x32_bf16 v[104:107], v[136:139], v[186:189], 0
	v_mfma_f32_16x16x32_bf16 v[92:95], v[128:131], v[194:197], 0
	v_mfma_f32_16x16x32_bf16 v[88:91], v[136:139], v[194:197], 0
	v_mfma_f32_16x16x32_bf16 v[76:79], v[128:131], v[202:205], 0
	v_mfma_f32_16x16x32_bf16 v[72:75], v[136:139], v[202:205], 0
	v_mfma_f32_16x16x32_bf16 v[124:127], v[132:135], v[182:185], v[124:127]
	v_mfma_f32_16x16x32_bf16 v[120:123], v[140:143], v[182:185], v[120:123]
	v_mfma_f32_16x16x32_bf16 v[108:111], v[132:135], v[190:193], v[108:111]
	v_mfma_f32_16x16x32_bf16 v[104:107], v[140:143], v[190:193], v[104:107]
	v_mfma_f32_16x16x32_bf16 v[92:95], v[132:135], v[198:201], v[92:95]
	v_mfma_f32_16x16x32_bf16 v[88:91], v[140:143], v[198:201], v[88:91]
	v_mfma_f32_16x16x32_bf16 v[76:79], v[132:135], v[206:209], v[76:79]
	v_mfma_f32_16x16x32_bf16 v[72:75], v[140:143], v[206:209], v[72:75]
	s_setprio 0
	s_setprio 1
	v_mfma_f32_16x16x32_bf16 v[116:119], v[144:147], v[178:181], 0
	v_mfma_f32_16x16x32_bf16 v[112:115], v[164:167], v[178:181], 0
	v_mfma_f32_16x16x32_bf16 v[100:103], v[144:147], v[186:189], 0
	v_mfma_f32_16x16x32_bf16 v[96:99], v[164:167], v[186:189], 0
	v_mfma_f32_16x16x32_bf16 v[84:87], v[144:147], v[194:197], 0
	v_mfma_f32_16x16x32_bf16 v[80:83], v[164:167], v[194:197], 0
	v_mfma_f32_16x16x32_bf16 v[68:71], v[144:147], v[202:205], 0
	v_mfma_f32_16x16x32_bf16 v[64:67], v[164:167], v[202:205], 0
	v_mfma_f32_16x16x32_bf16 v[116:119], v[148:151], v[182:185], v[116:119]
	v_mfma_f32_16x16x32_bf16 v[112:115], v[168:171], v[182:185], v[112:115]
	v_mfma_f32_16x16x32_bf16 v[100:103], v[148:151], v[190:193], v[100:103]
	v_mfma_f32_16x16x32_bf16 v[96:99], v[168:171], v[190:193], v[96:99]
	v_mfma_f32_16x16x32_bf16 v[84:87], v[148:151], v[198:201], v[84:87]
	v_mfma_f32_16x16x32_bf16 v[80:83], v[168:171], v[198:201], v[80:83]
	v_mfma_f32_16x16x32_bf16 v[68:71], v[148:151], v[206:209], v[68:71]
	v_mfma_f32_16x16x32_bf16 v[64:67], v[168:171], v[206:209], v[64:67]
	s_setprio 0
	s_barrier
	s_add_i32 s62, s52, s34
	v_lshl_add_u64 v[210:211], s[24:25], 0, v[152:153]
	s_mov_b32 m0, s62
	ds_read_b128 v[178:181], v177 offset:16384
	ds_read_b128 v[182:185], v177 offset:17408
	ds_read_b128 v[186:189], v177 offset:18432
	ds_read_b128 v[190:193], v177 offset:19456
	ds_read_b128 v[194:197], v177 offset:20480
	ds_read_b128 v[198:201], v177 offset:21504
	ds_read_b128 v[202:205], v177 offset:22528
	ds_read_b128 v[206:209], v177 offset:23552
	global_load_lds_dwordx4 v[210:211], off
	s_add_i32 m0, s62, 0x2000
	s_add_u32 s62, s24, 0x40000
	v_lshl_add_u64 v[212:213], s[24:25], 0, v[154:155]
	s_addc_u32 s63, s25, 0
	s_add_i32 s64, s53, s34
	global_load_lds_dwordx4 v[212:213], off
	v_lshl_add_u64 v[214:215], s[62:63], 0, v[152:153]
	s_mov_b32 m0, s64
	v_lshl_add_u64 v[216:217], s[26:27], 0, v[154:155]
	global_load_lds_dwordx4 v[214:215], off
	v_lshl_add_u64 v[214:215], s[62:63], 0, v[154:155]
	s_add_i32 m0, s64, 0x2000
	s_nop 0
	global_load_lds_dwordx4 v[214:215], off
	v_lshl_add_u64 v[214:215], s[26:27], 0, v[152:153]
	s_mov_b32 m0, s36
	s_nop 0
	global_load_lds_dwordx4 v[214:215], off
	s_mov_b32 m0, s37
	s_nop 0
	global_load_lds_dwordx4 v[216:217], off
	s_waitcnt vmcnt(8)
	s_waitcnt lgkmcnt(0)
	s_barrier
; #define PG8_STAGE(bufoff, gbase, voff) do { _Pragma("unroll") for (int _i = 0; _i < 2; ++_i) \
;         __builtin_amdgcn_global_load_lds((const unsigned*)((const char*)(gbase) + (voff)[_i]), (PG8_LAS unsigned*)(lds + (bufoff) + ldsw + _i * 8192), 16, 0, 0); } while (0)
; #define PG8_LDA(dst, b, h) do { _Pragma("unroll") for (int m = 0; m < 4; ++m) _Pragma("unroll") for (int k = 0; k < 2; ++k) dst[m][k] = *(const PG8_LAS bf16x8*)(lds + PG8_SA(b, h) + aoff + m * 2048 + k * 1024); } while (0)
; #define PG8_LDB(dst, b, h) do { _Pragma("unroll") for (int n = 0; n < 2; ++n) _Pragma("unroll") for (int k = 0; k < 2; ++k) dst[n][k] = *(const PG8_LAS bf16x8*)(lds + PG8_SB(b, h) + boff + n * 2048 + k * 1024); } while (0)
; #define PG8_MMA(ai, bj, At, Bt) do { __builtin_amdgcn_s_setprio(1); _Pragma("unroll") for (int m = 0; m < 4; ++m) _Pragma("unroll") for (int n = 0; n < 2; ++n) _Pragma("unroll") for (int k = 0; k < 2; ++k) \
;         acc[ai][bj][m][n] = __builtin_amdgcn_mfma_f32_16x16x32_bf16(Bt[n][k], At[m][k], acc[ai][bj][m][n], 0, 0, 0); __builtin_amdgcn_s_setprio(0); } while (0)
; #define PG8_WAIT_V(n) asm volatile("s_waitcnt vmcnt(" #n ")" ::: "memory")
; #define PG8_WAIT_L(n) asm volatile("s_waitcnt lgkmcnt(" #n ")" ::: "memory")
; #define PG8_BAR __builtin_amdgcn_s_barrier()
; #define PG8_SCHED __builtin_amdgcn_sched_barrier(0)
; template <class Epi, class Sched, bool ALIGN_EPI = false, bool SP2 = false>
; __device__ __forceinline__ void gemm_phase(PG8_LAS unsigned char* lds, const Gemm g, const Sched& S, const Epi& E) {
;     ...
;             PG8_WAIT_V(8); PG8_WAIT_L(0); PG8_BAR; PG8_MMA(1, 0, At, B0); PG8_MMA(1, 1, At, B1); PG8_BAR; PG8_SCHED;
;             PG8_LDB(B0, 1, 0); PG8_LDB(B1, 1, 1); PG8_SCHED; PG8_LDA(At, 1, 0); PG8_STAGE(PG8_SA(0, 1), a2 + hstep, voffA);
;             PG8_WAIT_V(8); PG8_WAIT_L(0); PG8_BAR; PG8_MMA(0, 0, At, B0); PG8_MMA(0, 1, At, B1); PG8_BAR; PG8_SCHED;
	s_setprio 1
	s_waitcnt lgkmcnt(0)
	v_mfma_f32_16x16x32_bf16 v[60:63], v[128:131], v[178:181], 0
	v_mfma_f32_16x16x32_bf16 v[56:59], v[136:139], v[178:181], 0
	v_mfma_f32_16x16x32_bf16 v[44:47], v[128:131], v[186:189], 0
	v_mfma_f32_16x16x32_bf16 v[40:43], v[136:139], v[186:189], 0
	v_mfma_f32_16x16x32_bf16 v[28:31], v[128:131], v[194:197], 0
	v_mfma_f32_16x16x32_bf16 v[24:27], v[136:139], v[194:197], 0
	v_mfma_f32_16x16x32_bf16 v[12:15], v[128:131], v[202:205], 0
	v_mfma_f32_16x16x32_bf16 v[8:11], v[136:139], v[202:205], 0
	v_mfma_f32_16x16x32_bf16 v[60:63], v[132:135], v[182:185], v[60:63]
	v_mfma_f32_16x16x32_bf16 v[56:59], v[140:143], v[182:185], v[56:59]
	v_mfma_f32_16x16x32_bf16 v[44:47], v[132:135], v[190:193], v[44:47]
	v_mfma_f32_16x16x32_bf16 v[40:43], v[140:143], v[190:193], v[40:43]
	v_mfma_f32_16x16x32_bf16 v[28:31], v[132:135], v[198:201], v[28:31]
	v_mfma_f32_16x16x32_bf16 v[24:27], v[140:143], v[198:201], v[24:27]
	v_mfma_f32_16x16x32_bf16 v[12:15], v[132:135], v[206:209], v[12:15]
	v_mfma_f32_16x16x32_bf16 v[8:11], v[140:143], v[206:209], v[8:11]
	s_setprio 0
	s_setprio 1
	v_mfma_f32_16x16x32_bf16 v[52:55], v[144:147], v[178:181], 0
	v_mfma_f32_16x16x32_bf16 v[48:51], v[164:167], v[178:181], 0
	v_mfma_f32_16x16x32_bf16 v[36:39], v[144:147], v[186:189], 0
	v_mfma_f32_16x16x32_bf16 v[32:35], v[164:167], v[186:189], 0
	v_mfma_f32_16x16x32_bf16 v[20:23], v[144:147], v[194:197], 0
	v_mfma_f32_16x16x32_bf16 v[16:19], v[164:167], v[194:197], 0
	v_mfma_f32_16x16x32_bf16 v[4:7], v[144:147], v[202:205], 0
	v_mfma_f32_16x16x32_bf16 v[0:3], v[164:167], v[202:205], 0
	v_mfma_f32_16x16x32_bf16 v[52:55], v[148:151], v[182:185], v[52:55]
	v_mfma_f32_16x16x32_bf16 v[48:51], v[168:171], v[182:185], v[48:51]
	v_mfma_f32_16x16x32_bf16 v[36:39], v[148:151], v[190:193], v[36:39]
	v_mfma_f32_16x16x32_bf16 v[32:35], v[168:171], v[190:193], v[32:35]
	v_mfma_f32_16x16x32_bf16 v[20:23], v[148:151], v[198:201], v[20:23]
	v_mfma_f32_16x16x32_bf16 v[16:19], v[168:171], v[198:201], v[16:19]
	v_mfma_f32_16x16x32_bf16 v[4:7], v[148:151], v[206:209], v[4:7]
	v_mfma_f32_16x16x32_bf16 v[0:3], v[168:171], v[206:209], v[0:3]
	s_setprio 0
	s_barrier
	s_add_i32 s62, 0, 0x18000
	s_add_i32 s63, 0, 0x1c000
	v_add_u32_e32 v140, s62, v174
	v_add_u32_e32 v168, s63, v174
	ds_read_b128 v[128:131], v140
	ds_read_b128 v[132:135], v140 offset:1024
	ds_read_b128 v[136:139], v140 offset:2048
	ds_read_b128 v[140:143], v140 offset:3072
	ds_read_b128 v[144:147], v168
	ds_read_b128 v[148:151], v168 offset:1024
	ds_read_b128 v[164:167], v168 offset:2048
	ds_read_b128 v[168:171], v168 offset:3072
	s_add_u32 s26, s26, 0x40000
	s_addc_u32 s27, s27, 0
	s_mov_b32 m0, s38
	v_lshl_add_u64 v[218:219], s[26:27], 0, v[152:153]
	ds_read_b128 v[178:181], v177 offset:32768
	ds_read_b128 v[182:185], v177 offset:33792
	ds_read_b128 v[186:189], v177 offset:34816
	ds_read_b128 v[190:193], v177 offset:35840
	ds_read_b128 v[194:197], v177 offset:36864
	ds_read_b128 v[198:201], v177 offset:37888
	ds_read_b128 v[202:205], v177 offset:38912
	ds_read_b128 v[206:209], v177 offset:39936
	global_load_lds_dwordx4 v[218:219], off
	v_lshl_add_u64 v[218:219], s[26:27], 0, v[154:155]
	s_mov_b32 m0, s39
	s_nop 0
	global_load_lds_dwordx4 v[218:219], off
	s_waitcnt vmcnt(8)
	s_waitcnt lgkmcnt(0)
	s_barrier
	s_setprio 1
	s_waitcnt lgkmcnt(0)
	v_mfma_f32_16x16x32_bf16 v[124:127], v[128:131], v[178:181], v[124:127]
	v_mfma_f32_16x16x32_bf16 v[120:123], v[136:139], v[178:181], v[120:123]
	v_mfma_f32_16x16x32_bf16 v[108:111], v[128:131], v[186:189], v[108:111]
	v_mfma_f32_16x16x32_bf16 v[104:107], v[136:139], v[186:189], v[104:107]
	v_mfma_f32_16x16x32_bf16 v[92:95], v[128:131], v[194:197], v[92:95]
	v_mfma_f32_16x16x32_bf16 v[88:91], v[136:139], v[194:197], v[88:91]
	v_mfma_f32_16x16x32_bf16 v[76:79], v[128:131], v[202:205], v[76:79]
	v_mfma_f32_16x16x32_bf16 v[72:75], v[136:139], v[202:205], v[72:75]
	v_mfma_f32_16x16x32_bf16 v[124:127], v[132:135], v[182:185], v[124:127]
	v_mfma_f32_16x16x32_bf16 v[120:123], v[140:143], v[182:185], v[120:123]
	v_mfma_f32_16x16x32_bf16 v[108:111], v[132:135], v[190:193], v[108:111]
	v_mfma_f32_16x16x32_bf16 v[104:107], v[140:143], v[190:193], v[104:107]
	v_mfma_f32_16x16x32_bf16 v[92:95], v[132:135], v[198:201], v[92:95]
	v_mfma_f32_16x16x32_bf16 v[88:91], v[140:143], v[198:201], v[88:91]
	v_mfma_f32_16x16x32_bf16 v[76:79], v[132:135], v[206:209], v[76:79]
	v_mfma_f32_16x16x32_bf16 v[72:75], v[140:143], v[206:209], v[72:75]
	s_setprio 0
	s_setprio 1
	v_mfma_f32_16x16x32_bf16 v[116:119], v[144:147], v[178:181], v[116:119]
	v_mfma_f32_16x16x32_bf16 v[112:115], v[164:167], v[178:181], v[112:115]
	v_mfma_f32_16x16x32_bf16 v[100:103], v[144:147], v[186:189], v[100:103]
	v_mfma_f32_16x16x32_bf16 v[96:99], v[164:167], v[186:189], v[96:99]
	v_mfma_f32_16x16x32_bf16 v[84:87], v[144:147], v[194:197], v[84:87]
	v_mfma_f32_16x16x32_bf16 v[80:83], v[164:167], v[194:197], v[80:83]
	v_mfma_f32_16x16x32_bf16 v[68:71], v[144:147], v[202:205], v[68:71]
	v_mfma_f32_16x16x32_bf16 v[64:67], v[164:167], v[202:205], v[64:67]
	v_mfma_f32_16x16x32_bf16 v[116:119], v[148:151], v[182:185], v[116:119]
	v_mfma_f32_16x16x32_bf16 v[112:115], v[168:171], v[182:185], v[112:115]
	v_mfma_f32_16x16x32_bf16 v[100:103], v[148:151], v[190:193], v[100:103]
	v_mfma_f32_16x16x32_bf16 v[96:99], v[168:171], v[190:193], v[96:99]
	v_mfma_f32_16x16x32_bf16 v[84:87], v[148:151], v[198:201], v[84:87]
	v_mfma_f32_16x16x32_bf16 v[80:83], v[168:171], v[198:201], v[80:83]
	v_mfma_f32_16x16x32_bf16 v[68:71], v[148:151], v[206:209], v[68:71]
	v_mfma_f32_16x16x32_bf16 v[64:67], v[168:171], v[206:209], v[64:67]
	s_setprio 0
	s_barrier
; #define PG8_STAGE(bufoff, gbase, voff) do { _Pragma("unroll") for (int _i = 0; _i < 2; ++_i) \
;         __builtin_amdgcn_global_load_lds((const unsigned*)((const char*)(gbase) + (voff)[_i]), (PG8_LAS unsigned*)(lds + (bufoff) + ldsw + _i * 8192), 16, 0, 0); } while (0)
; #define PG8_LDA(dst, b, h) do { _Pragma("unroll") for (int m = 0; m < 4; ++m) _Pragma("unroll") for (int k = 0; k < 2; ++k) dst[m][k] = *(const PG8_LAS bf16x8*)(lds + PG8_SA(b, h) + aoff + m * 2048 + k * 1024); } while (0)
; #define PG8_MMA(ai, bj, At, Bt) do { __builtin_amdgcn_s_setprio(1); _Pragma("unroll") for (int m = 0; m < 4; ++m) _Pragma("unroll") for (int n = 0; n < 2; ++n) _Pragma("unroll") for (int k = 0; k < 2; ++k) \
;         acc[ai][bj][m][n] = __builtin_amdgcn_mfma_f32_16x16x32_bf16(Bt[n][k], At[m][k], acc[ai][bj][m][n], 0, 0, 0); __builtin_amdgcn_s_setprio(0); } while (0)
; #define PG8_WAIT_V(n) asm volatile("s_waitcnt vmcnt(" #n ")" ::: "memory")
; #define PG8_WAIT_L(n) asm volatile("s_waitcnt lgkmcnt(" #n ")" ::: "memory")
; #define PG8_BAR __builtin_amdgcn_s_barrier()
; #define PG8_SCHED __builtin_amdgcn_sched_barrier(0)
; template <class Epi, class Sched, bool ALIGN_EPI = false, bool SP2 = false>
; __device__ __forceinline__ void gemm_phase(PG8_LAS unsigned char* lds, const Gemm g, const Sched& S, const Epi& E) {
;     ...
;         for (int t = 0; t < nt; t += 2) {
;             const bool last = (t == nt - 2);
;             const char* a1 = cA + (size_t)(t + 1) * kstep;
;             const char* a2 = last ? nA : cA + (size_t)(t + 2) * kstep; const char* b2 = last ? nB : cB + (size_t)(t + 2) * kstep;
;     ...
;             PG8_LDA(At, 1, 1); PG8_STAGE(PG8_SB(1, 0), b3, voffB); PG8_STAGE(PG8_SB(1, 1), b3 + hstep, voffB); PG8_STAGE(PG8_SA(1, 0), a3, voffA);
;             PG8_WAIT_V(8); PG8_WAIT_L(0); PG8_BAR; PG8_MMA(1, 0, At, B0); PG8_MMA(1, 1, At, B1); PG8_BAR; PG8_SCHED;
	s_add_i32 s26, s62, s34
	v_lshl_add_u64 v[210:211], v[210:211], 0, s[10:11]
	s_mov_b32 m0, s26
	ds_read_b128 v[178:181], v177 offset:49152
	ds_read_b128 v[182:185], v177 offset:50176
	ds_read_b128 v[186:189], v177 offset:51200
	ds_read_b128 v[190:193], v177 offset:52224
	ds_read_b128 v[194:197], v177 offset:53248
	ds_read_b128 v[198:201], v177 offset:54272
	ds_read_b128 v[202:205], v177 offset:55296
	ds_read_b128 v[206:209], v177 offset:56320
	global_load_lds_dwordx4 v[210:211], off
	s_add_i32 m0, s26, 0x2000
	s_add_u32 s24, s24, 0x40080
	v_lshl_add_u64 v[210:211], v[212:213], 0, s[10:11]
	s_addc_u32 s25, s25, 0
	s_add_i32 s26, s63, s34
	global_load_lds_dwordx4 v[210:211], off
	v_lshl_add_u64 v[210:211], s[24:25], 0, v[152:153]
	s_mov_b32 m0, s26
	s_nop 0
	global_load_lds_dwordx4 v[210:211], off
	v_lshl_add_u64 v[210:211], s[24:25], 0, v[154:155]
	s_add_i32 m0, s26, 0x2000
	s_nop 0
	global_load_lds_dwordx4 v[210:211], off
	v_lshl_add_u64 v[210:211], v[214:215], 0, s[10:11]
	s_mov_b32 m0, s45
	s_nop 0
	global_load_lds_dwordx4 v[210:211], off
	v_lshl_add_u64 v[210:211], v[216:217], 0, s[10:11]
	s_mov_b32 m0, s46
	s_nop 0
	global_load_lds_dwordx4 v[210:211], off
	s_waitcnt vmcnt(8)
	s_waitcnt lgkmcnt(0)
	s_barrier
	s_setprio 1
	s_waitcnt lgkmcnt(0)
	v_mfma_f32_16x16x32_bf16 v[60:63], v[128:131], v[178:181], v[60:63]
	v_mfma_f32_16x16x32_bf16 v[56:59], v[136:139], v[178:181], v[56:59]
	v_mfma_f32_16x16x32_bf16 v[44:47], v[128:131], v[186:189], v[44:47]
	v_mfma_f32_16x16x32_bf16 v[40:43], v[136:139], v[186:189], v[40:43]
	v_mfma_f32_16x16x32_bf16 v[28:31], v[128:131], v[194:197], v[28:31]
	v_mfma_f32_16x16x32_bf16 v[24:27], v[136:139], v[194:197], v[24:27]
	v_mfma_f32_16x16x32_bf16 v[12:15], v[128:131], v[202:205], v[12:15]
	v_mfma_f32_16x16x32_bf16 v[8:11], v[136:139], v[202:205], v[8:11]
	v_mfma_f32_16x16x32_bf16 v[60:63], v[132:135], v[182:185], v[60:63]
	v_mfma_f32_16x16x32_bf16 v[56:59], v[140:143], v[182:185], v[56:59]
	v_mfma_f32_16x16x32_bf16 v[44:47], v[132:135], v[190:193], v[44:47]
	v_mfma_f32_16x16x32_bf16 v[40:43], v[140:143], v[190:193], v[40:43]
	v_mfma_f32_16x16x32_bf16 v[28:31], v[132:135], v[198:201], v[28:31]
	v_mfma_f32_16x16x32_bf16 v[24:27], v[140:143], v[198:201], v[24:27]
	v_mfma_f32_16x16x32_bf16 v[12:15], v[132:135], v[206:209], v[12:15]
	v_mfma_f32_16x16x32_bf16 v[8:11], v[140:143], v[206:209], v[8:11]
	s_setprio 0
	s_setprio 1
	v_mfma_f32_16x16x32_bf16 v[52:55], v[144:147], v[178:181], v[52:55]
	v_mfma_f32_16x16x32_bf16 v[48:51], v[164:167], v[178:181], v[48:51]
	v_mfma_f32_16x16x32_bf16 v[36:39], v[144:147], v[186:189], v[36:39]
	v_mfma_f32_16x16x32_bf16 v[32:35], v[164:167], v[186:189], v[32:35]
	v_mfma_f32_16x16x32_bf16 v[20:23], v[144:147], v[194:197], v[20:23]
	v_mfma_f32_16x16x32_bf16 v[16:19], v[164:167], v[194:197], v[16:19]
	v_mfma_f32_16x16x32_bf16 v[4:7], v[144:147], v[202:205], v[4:7]
	v_mfma_f32_16x16x32_bf16 v[0:3], v[164:167], v[202:205], v[0:3]
	v_mfma_f32_16x16x32_bf16 v[52:55], v[148:151], v[182:185], v[52:55]
	v_mfma_f32_16x16x32_bf16 v[48:51], v[168:171], v[182:185], v[48:51]
	v_mfma_f32_16x16x32_bf16 v[36:39], v[148:151], v[190:193], v[36:39]
	v_mfma_f32_16x16x32_bf16 v[32:35], v[168:171], v[190:193], v[32:35]
	v_mfma_f32_16x16x32_bf16 v[20:23], v[148:151], v[198:201], v[20:23]
	v_mfma_f32_16x16x32_bf16 v[16:19], v[168:171], v[198:201], v[16:19]
	v_mfma_f32_16x16x32_bf16 v[4:7], v[148:151], v[206:209], v[4:7]
	v_mfma_f32_16x16x32_bf16 v[0:3], v[168:171], v[206:209], v[0:3]
	s_setprio 0
	s_barrier
	s_add_i32 s61, s61, 2
	s_add_u32 s22, s22, 0x100
	s_addc_u32 s23, s23, 0
	s_add_u32 s59, s59, 0x100
	s_addc_u32 s60, s60, 0
	s_cmp_gt_u32 s61, 13
